# P6 epilogue loads hoisted; L2 write-back skipped (run-time XCC check) at the 5 grid barriers whose consumers are the producers' own row group
# speedup vs baseline: 1.0344x; 1.0114x over previous
_Z14fwd_megakernel4Args:
	s_mov_b32 s100, 0
	s_load_dwordx2 s[28:29], s[0:1], 0xb8
	s_add_u32 s8, s0, 0xb8
	s_addc_u32 s9, s1, 0
	v_and_b32_e32 v208, 0x3ff, v0
	s_mov_b32 s93, s2
	s_waitcnt lgkmcnt(0)
	s_mov_b32 s3, s28
	v_writelane_b32 v255, s3, 0
	s_and_b32 s3, s28, 7
	v_readfirstlane_b32 s79, v208
	s_cmp_lg_u32 s3, 0
	s_cbranch_scc1 .LBB0_2
	s_ashr_i32 s4, s2, 31
	s_lshr_b32 s4, s4, 29
	s_add_i32 s4, s2, s4
	s_and_b32 s5, s4, -8
	s_ashr_i32 s3, s28, 3
	s_sub_i32 s5, s2, s5
	s_mul_i32 s3, s3, s5
	s_ashr_i32 s4, s4, 3
	s_add_i32 s93, s3, s4

.LBB0_24:
	s_or_b64 exec, exec, s[6:7]
	s_mov_b64 s[6:7], s[0:1]
	s_barrier
	s_load_dwordx2 s[30:31], s[6:7], 0xa8
	s_getreg_b32 s60, hwreg(HW_REG_XCC_ID, 0, 4)
	v_cmp_eq_u32_e64 s[26:27], 0, v208
	s_waitcnt lgkmcnt(0)
	s_add_u32 s34, s30, 0x40000
	s_addc_u32 s35, s31, 0
	s_and_b32 s33, s60, 15
	s_and_saveexec_b64 s[6:7], s[26:27]
	s_cbranch_execz .LBB0_27
	s_mov_b64 s[8:9], exec
	v_mbcnt_lo_u32_b32 v0, s8, 0
	v_mbcnt_hi_u32_b32 v0, s9, v0
	v_cmp_eq_u32_e32 vcc, 0, v0
	s_and_b64 s[10:11], exec, vcc
	s_mov_b64 exec, s[10:11]
	s_cbranch_execz .LBB0_27
	s_lshl_b32 s10, s33, 8
	s_bcnt1_i32_b64 s8, s[8:9]
	v_mov_b32_e32 v0, s10
	v_mov_b32_e32 v1, s8
	global_atomic_add v0, v1, s[34:35] offset:1024
	s_lshl_b32 s98, s2, 2
	s_add_i32 s98, s98, 0x8000
	v_mov_b32_e32 v0, s98
	v_mov_b32_e32 v1, s33
	global_store_dword v0, v1, s[34:35]

.LBB0_167:
	s_or_b64 exec, exec, s[8:9]
	s_waitcnt lgkmcnt(0)
	s_barrier
	s_mov_b32 s100, 0
	s_cmpk_lg_u32 s28, 0x100
	s_cbranch_scc1 .Lwb_chk_done
	v_mbcnt_lo_u32_b32 v0, -1, 0
	v_mbcnt_hi_u32_b32 v0, -1, v0
	v_lshlrev_b32_e32 v0, 2, v0
	s_add_u32 s98, s34, 0x8000
	s_addc_u32 s99, s35, 0
	global_load_dword v1, v0, s[98:99] sc1
	global_load_dword v2, v0, s[98:99] offset:256 sc1
	global_load_dword v3, v0, s[98:99] offset:512 sc1
	global_load_dword v4, v0, s[98:99] offset:768 sc1
	s_waitcnt vmcnt(0)
	v_cmp_eq_u32_e32 vcc, v1, v2
	v_cmp_eq_u32_e64 s[98:99], v1, v3
	s_nop 3
	s_and_b64 vcc, vcc, s[98:99]
	v_cmp_eq_u32_e64 s[98:99], v1, v4
	s_nop 3
	s_and_b64 vcc, vcc, s[98:99]
	s_cmp_eq_u64 vcc, exec
	s_cselect_b32 s100, 1, 0
.Lwb_chk_done:
.LBB0_168:
	s_cmp_lt_i32 s3, 2
	s_cselect_b64 s[8:9], -1, 0
	s_and_b64 s[36:37], s[8:9], s[6:7]
	s_andn2_b64 vcc, exec, s[36:37]
	s_cbranch_vccnz .LBB0_226
	s_mov_b64 s[6:7], s[0:1]
	s_cmp_gt_i32 s2, 63
	s_cbranch_scc1 .LBB0_182
	s_load_dwordx2 s[6:7], s[6:7], 0xa8
	v_lshlrev_b32_e32 v0, 5, v208
	s_waitcnt lgkmcnt(0)
	v_mov_b32_e32 v1, 0
	s_mov_b64 s[8:9], 0x100000
	v_mbcnt_lo_u32_b32 v2, -1, 0
	v_lshl_add_u64 v[0:1], s[6:7], 0, v[0:1]
	v_lshl_add_u64 v[4:5], v[0:1], 0, s[8:9]
	s_lshl_b32 s8, s96, 2
	v_mbcnt_hi_u32_b32 v2, -1, v2
	s_add_i32 s39, s8, 0
	s_mov_b64 s[8:9], 0x200000
	v_and_b32_e32 v3, 64, v2
	v_lshl_add_u64 v[6:7], v[0:1], 0, s[8:9]
	v_add_u32_e32 v0, -1, v2
	v_cmp_lt_i32_e32 vcc, v0, v3
	s_add_i32 s39, s39, 0x22000
	s_cmp_gt_u32 s79, 63
	v_cndmask_b32_e32 v0, v0, v2, vcc
	v_lshlrev_b32_e32 v13, 2, v0
	v_add_u32_e32 v0, -2, v2
	v_cmp_lt_i32_e32 vcc, v0, v3
	s_cselect_b64 s[20:21], -1, 0
	s_add_i32 s22, s96, -1
	v_cndmask_b32_e32 v0, v0, v2, vcc
	v_lshlrev_b32_e32 v14, 2, v0
	v_add_u32_e32 v0, -4, v2
	v_cmp_lt_i32_e32 vcc, v0, v3
	s_bfe_u32 s44, s79, 0x30006
	s_cmp_gt_u32 s22, 6
	v_cndmask_b32_e32 v0, v0, v2, vcc
	v_lshlrev_b32_e32 v15, 2, v0
	v_add_u32_e32 v0, -8, v2
	v_cmp_lt_i32_e32 vcc, v0, v3
	s_cselect_b64 s[22:23], -1, 0
	s_and_b32 s45, s96, 0x3fffff8
	v_cndmask_b32_e32 v0, v0, v2, vcc
	v_lshlrev_b32_e32 v16, 2, v0
	v_add_u32_e32 v0, -16, v2
	v_cmp_lt_i32_e32 vcc, v0, v3
	s_cmp_lg_u32 s44, 0
	s_cselect_b64 s[24:25], -1, 0
	v_cndmask_b32_e32 v0, v0, v2, vcc
	v_lshlrev_b32_e32 v17, 2, v0
	v_subrev_u32_e32 v0, 32, v2
	v_cmp_lt_i32_e32 vcc, v0, v3
	v_cmp_eq_u32_e64 s[6:7], 63, v210
	v_cmp_eq_u32_e64 s[8:9], 0, v210
	v_cndmask_b32_e32 v0, v0, v2, vcc
	v_lshlrev_b32_e32 v18, 2, v0
	v_cndmask_b32_e64 v0, 0, 1, s[20:21]
	v_cmp_ne_u32_e64 s[20:21], 1, v0
	v_cndmask_b32_e64 v0, 0, 1, s[22:23]
	v_cmp_ne_u32_e64 s[22:23], 1, v0
	v_cndmask_b32_e64 v0, 0, 1, s[24:25]
	v_cmp_gt_u32_e64 s[10:11], 2, v210
	v_cmp_gt_u32_e64 s[12:13], 4, v210
	v_cmp_gt_u32_e64 s[14:15], 8, v210
	v_cmp_gt_u32_e64 s[16:17], 16, v210
	v_cmp_gt_u32_e64 s[18:19], 32, v210
	s_add_i32 s46, 0, 0x22000
	v_cmp_ne_u32_e64 s[24:25], 1, v0
	s_mov_b32 s38, 0xbfb8aa3b
	s_mov_b32 s40, s2
	s_branch .LBB0_172

.LBB0_663:
	s_andn2_saveexec_b64 s[10:11], s[10:11]
	s_cbranch_execz .LBB0_683
	s_mov_b64 s[10:11], exec
	s_cmp_lg_u32 s100, 0
	s_cbranch_scc1 .Lwb_skip_3
	buffer_wbl2 sc1
.Lwb_skip_3:
	s_waitcnt lgkmcnt(0)
	s_waitcnt vmcnt(0)
	v_mbcnt_lo_u32_b32 v1, s10, 0
	v_mbcnt_hi_u32_b32 v1, s11, v1
	v_cmp_eq_u32_e32 vcc, 0, v1
	s_and_saveexec_b64 s[12:13], vcc
	s_cbranch_execz .LBB0_666
	s_bcnt1_i32_b64 s10, s[10:11]
	v_mov_b32_e32 v2, 0x43000
	v_mov_b32_e32 v3, s10
	global_atomic_add v2, v2, v3, s[30:31] offset:1024 sc0

.LBB0_905:
	s_lshl_b32 s17, s24, 8
	s_add_i32 s17, s17, s52
	v_or_b32_e32 v146, s17, v150
	v_ashrrev_i32_e32 v147, 31, v146
	v_lshl_add_u64 v[148:149], v[146:147], 2, s[10:11]
	global_load_dword v246, v[148:149], off
	global_load_dword v247, v[148:149], off offset:64
	global_load_dword v248, v[148:149], off offset:128
	global_load_dword v249, v[148:149], off offset:192
	global_load_dword v250, v[148:149], off offset:512
	global_load_dword v251, v[148:149], off offset:576
	global_load_dword v252, v[148:149], off offset:640
	global_load_dword v253, v[148:149], off offset:704
	s_nop 0
	s_lshl_b32 s19, s60, 14
	v_bitop3_b32 v147, s19, v157, v156 bitop3:0xc8
	s_ashr_i32 s17, s17, 4
	v_or_b32_e32 v158, 0x2000, v147
	v_add_u32_e32 v161, s17, v147
	v_add_u32_e32 v165, s17, v158
	v_or_b32_e32 v160, 16, v146
	v_mad_i64_i32 v[162:163], s[36:37], v161, s59, v[136:137]
	v_mad_i64_i32 v[166:167], s[36:37], v165, s59, v[136:137]
	v_ashrrev_i32_e32 v161, 31, v160
	v_lshl_add_u64 v[168:169], v[160:161], 2, s[10:11]
	s_andn2_b64 vcc, exec, s[4:5]
	s_waitcnt vmcnt(0)
	v_mov_b32_e32 v159, v246
	v_fmamk_f32 v159, v159, 0x3a800000, v155
	v_rsq_f32_e32 v164, v159
	s_nop 0
	v_pk_mul_f32 v[126:127], v[126:127], v[164:165] op_sel_hi:[1,0]
	v_pk_mul_f32 v[124:125], v[124:125], v[164:165] op_sel_hi:[1,0]
	v_pk_mul_f32 v[122:123], v[122:123], v[164:165] op_sel_hi:[1,0]
	v_pk_mul_f32 v[120:121], v[120:121], v[164:165] op_sel_hi:[1,0]
	v_pk_mul_f32 v[118:119], v[118:119], v[164:165] op_sel_hi:[1,0]
	v_pk_mul_f32 v[116:117], v[116:117], v[164:165] op_sel_hi:[1,0]
	v_pk_mul_f32 v[170:171], v[114:115], v[164:165] op_sel_hi:[1,0]
	v_pk_mul_f32 v[164:165], v[112:113], v[164:165] op_sel_hi:[1,0]
	v_cvt_pk_bf16_f32 v112, v124, v125
	v_cvt_pk_bf16_f32 v113, v126, v127
	v_cvt_pk_bf16_f32 v114, v120, v121
	v_cvt_pk_bf16_f32 v115, v122, v123
	global_store_dwordx4 v[162:163], v[112:115], off
	s_nop 1
	v_cvt_pk_bf16_f32 v112, v116, v117
	v_cvt_pk_bf16_f32 v113, v118, v119
	v_cvt_pk_bf16_f32 v114, v164, v165
	v_cvt_pk_bf16_f32 v115, v170, v171
	global_store_dwordx4 v[166:167], v[112:115], off
	s_nop 0
	s_nop 0
	v_or_b32_e32 v112, 32, v146
	v_ashrrev_i32_e32 v114, 4, v160
	v_ashrrev_i32_e32 v113, 31, v112
	v_add_u32_e32 v117, v114, v147
	v_add_u32_e32 v120, v158, v114
	v_lshl_add_u64 v[114:115], v[112:113], 2, s[10:11]
	v_mad_i64_i32 v[118:119], s[36:37], v117, s59, v[136:137]
	v_mad_i64_i32 v[120:121], s[36:37], v120, s59, v[136:137]
	v_mov_b32_e32 v116, v247
	v_fmamk_f32 v113, v116, 0x3a800000, v155
	v_rsq_f32_e32 v116, v113
	s_nop 0
	v_pk_mul_f32 v[110:111], v[110:111], v[116:117] op_sel_hi:[1,0]
	v_pk_mul_f32 v[108:109], v[108:109], v[116:117] op_sel_hi:[1,0]
	v_pk_mul_f32 v[106:107], v[106:107], v[116:117] op_sel_hi:[1,0]
	v_pk_mul_f32 v[104:105], v[104:105], v[116:117] op_sel_hi:[1,0]
	v_pk_mul_f32 v[102:103], v[102:103], v[116:117] op_sel_hi:[1,0]
	v_pk_mul_f32 v[100:101], v[100:101], v[116:117] op_sel_hi:[1,0]
	v_pk_mul_f32 v[122:123], v[98:99], v[116:117] op_sel_hi:[1,0]
	v_pk_mul_f32 v[116:117], v[96:97], v[116:117] op_sel_hi:[1,0]
	v_cvt_pk_bf16_f32 v96, v108, v109
	v_cvt_pk_bf16_f32 v97, v110, v111
	v_cvt_pk_bf16_f32 v98, v104, v105
	v_cvt_pk_bf16_f32 v99, v106, v107
	global_store_dwordx4 v[118:119], v[96:99], off
	s_nop 1
	v_cvt_pk_bf16_f32 v96, v100, v101
	v_cvt_pk_bf16_f32 v97, v102, v103
	v_cvt_pk_bf16_f32 v98, v116, v117
	v_cvt_pk_bf16_f32 v99, v122, v123
	global_store_dwordx4 v[120:121], v[96:99], off
	s_nop 0
	s_nop 0
	v_or_b32_e32 v96, 48, v146
	v_ashrrev_i32_e32 v98, 4, v112
	v_ashrrev_i32_e32 v97, 31, v96
	v_add_u32_e32 v101, v98, v147
	v_add_u32_e32 v104, v158, v98
	v_lshl_add_u64 v[98:99], v[96:97], 2, s[10:11]
	v_mad_i64_i32 v[102:103], s[36:37], v101, s59, v[136:137]
	v_mad_i64_i32 v[104:105], s[36:37], v104, s59, v[136:137]
	v_mov_b32_e32 v100, v248
	v_fmamk_f32 v97, v100, 0x3a800000, v155
	v_rsq_f32_e32 v100, v97
	s_nop 0
	v_pk_mul_f32 v[94:95], v[94:95], v[100:101] op_sel_hi:[1,0]
	v_pk_mul_f32 v[92:93], v[92:93], v[100:101] op_sel_hi:[1,0]
	v_pk_mul_f32 v[90:91], v[90:91], v[100:101] op_sel_hi:[1,0]
	v_pk_mul_f32 v[88:89], v[88:89], v[100:101] op_sel_hi:[1,0]
	v_pk_mul_f32 v[86:87], v[86:87], v[100:101] op_sel_hi:[1,0]
	v_pk_mul_f32 v[84:85], v[84:85], v[100:101] op_sel_hi:[1,0]
	v_pk_mul_f32 v[106:107], v[82:83], v[100:101] op_sel_hi:[1,0]
	v_pk_mul_f32 v[100:101], v[80:81], v[100:101] op_sel_hi:[1,0]
	v_cvt_pk_bf16_f32 v80, v92, v93
	v_cvt_pk_bf16_f32 v81, v94, v95
	v_cvt_pk_bf16_f32 v82, v88, v89
	v_cvt_pk_bf16_f32 v83, v90, v91
	global_store_dwordx4 v[102:103], v[80:83], off
	s_nop 1
	v_cvt_pk_bf16_f32 v80, v84, v85
	v_cvt_pk_bf16_f32 v81, v86, v87
	v_cvt_pk_bf16_f32 v82, v100, v101
	v_cvt_pk_bf16_f32 v83, v106, v107
	global_store_dwordx4 v[104:105], v[80:83], off
	s_nop 0
	s_nop 0
	v_ashrrev_i32_e32 v81, 4, v96
	v_add_u32_e32 v82, v81, v147
	v_add_u32_e32 v81, v158, v81
	v_mad_i64_i32 v[82:83], s[36:37], v82, s59, v[136:137]
	v_mad_i64_i32 v[84:85], s[36:37], v81, s59, v[136:137]
	v_mov_b32_e32 v80, v249
	v_fmamk_f32 v80, v80, 0x3a800000, v155
	v_rsq_f32_e32 v80, v80
	s_nop 0
	v_pk_mul_f32 v[78:79], v[78:79], v[80:81] op_sel_hi:[1,0]
	v_pk_mul_f32 v[76:77], v[76:77], v[80:81] op_sel_hi:[1,0]
	v_pk_mul_f32 v[74:75], v[74:75], v[80:81] op_sel_hi:[1,0]
	v_pk_mul_f32 v[72:73], v[72:73], v[80:81] op_sel_hi:[1,0]
	v_pk_mul_f32 v[70:71], v[70:71], v[80:81] op_sel_hi:[1,0]
	v_pk_mul_f32 v[68:69], v[68:69], v[80:81] op_sel_hi:[1,0]
	v_pk_mul_f32 v[86:87], v[66:67], v[80:81] op_sel_hi:[1,0]
	v_pk_mul_f32 v[80:81], v[64:65], v[80:81] op_sel_hi:[1,0]
	v_cvt_pk_bf16_f32 v64, v76, v77
	v_cvt_pk_bf16_f32 v65, v78, v79
	v_cvt_pk_bf16_f32 v66, v72, v73
	v_cvt_pk_bf16_f32 v67, v74, v75
	global_store_dwordx4 v[82:83], v[64:67], off
	s_nop 1
	v_cvt_pk_bf16_f32 v64, v68, v69
	v_cvt_pk_bf16_f32 v65, v70, v71
	v_cvt_pk_bf16_f32 v66, v80, v81
	v_cvt_pk_bf16_f32 v67, v86, v87
	global_store_dwordx4 v[84:85], v[64:67], off
	s_nop 0
	s_nop 0
	v_add_u32_e32 v65, 0x80, v146
	v_ashrrev_i32_e32 v65, 4, v65
	v_add_u32_e32 v66, v65, v147
	v_add_u32_e32 v65, v158, v65
	v_mad_i64_i32 v[66:67], s[36:37], v66, s59, v[136:137]
	v_mad_i64_i32 v[68:69], s[36:37], v65, s59, v[136:137]
	v_mov_b32_e32 v64, v250
	v_fmamk_f32 v64, v64, 0x3a800000, v155
	v_rsq_f32_e32 v64, v64
	s_nop 0
	v_pk_mul_f32 v[62:63], v[62:63], v[64:65] op_sel_hi:[1,0]
	v_pk_mul_f32 v[60:61], v[60:61], v[64:65] op_sel_hi:[1,0]
	v_pk_mul_f32 v[58:59], v[58:59], v[64:65] op_sel_hi:[1,0]
	v_pk_mul_f32 v[56:57], v[56:57], v[64:65] op_sel_hi:[1,0]
	v_pk_mul_f32 v[54:55], v[54:55], v[64:65] op_sel_hi:[1,0]
	v_pk_mul_f32 v[52:53], v[52:53], v[64:65] op_sel_hi:[1,0]
	v_pk_mul_f32 v[70:71], v[50:51], v[64:65] op_sel_hi:[1,0]
	v_pk_mul_f32 v[64:65], v[48:49], v[64:65] op_sel_hi:[1,0]
	v_cvt_pk_bf16_f32 v48, v60, v61
	v_cvt_pk_bf16_f32 v49, v62, v63
	v_cvt_pk_bf16_f32 v50, v56, v57
	v_cvt_pk_bf16_f32 v51, v58, v59
	global_store_dwordx4 v[66:67], v[48:51], off
	s_nop 1
	v_cvt_pk_bf16_f32 v48, v52, v53
	v_cvt_pk_bf16_f32 v49, v54, v55
	v_cvt_pk_bf16_f32 v50, v64, v65
	v_cvt_pk_bf16_f32 v51, v70, v71
	global_store_dwordx4 v[68:69], v[48:51], off
	s_nop 0
	s_nop 0
	v_add_u32_e32 v49, 0x90, v146
	v_ashrrev_i32_e32 v49, 4, v49
	v_add_u32_e32 v50, v49, v147
	v_add_u32_e32 v49, v158, v49
	v_mad_i64_i32 v[50:51], s[36:37], v50, s59, v[136:137]
	v_mad_i64_i32 v[52:53], s[36:37], v49, s59, v[136:137]
	v_mov_b32_e32 v48, v251
	v_fmamk_f32 v48, v48, 0x3a800000, v155
	v_rsq_f32_e32 v48, v48
	s_nop 0
	v_pk_mul_f32 v[46:47], v[46:47], v[48:49] op_sel_hi:[1,0]
	v_pk_mul_f32 v[44:45], v[44:45], v[48:49] op_sel_hi:[1,0]
	v_pk_mul_f32 v[42:43], v[42:43], v[48:49] op_sel_hi:[1,0]
	v_pk_mul_f32 v[40:41], v[40:41], v[48:49] op_sel_hi:[1,0]
	v_pk_mul_f32 v[38:39], v[38:39], v[48:49] op_sel_hi:[1,0]
	v_pk_mul_f32 v[36:37], v[36:37], v[48:49] op_sel_hi:[1,0]
	v_pk_mul_f32 v[54:55], v[34:35], v[48:49] op_sel_hi:[1,0]
	v_pk_mul_f32 v[48:49], v[32:33], v[48:49] op_sel_hi:[1,0]
	v_cvt_pk_bf16_f32 v32, v44, v45
	v_cvt_pk_bf16_f32 v33, v46, v47
	v_cvt_pk_bf16_f32 v34, v40, v41
	v_cvt_pk_bf16_f32 v35, v42, v43
	global_store_dwordx4 v[50:51], v[32:35], off
	s_nop 1
	v_cvt_pk_bf16_f32 v32, v36, v37
	v_cvt_pk_bf16_f32 v33, v38, v39
	v_cvt_pk_bf16_f32 v34, v48, v49
	v_cvt_pk_bf16_f32 v35, v54, v55
	global_store_dwordx4 v[52:53], v[32:35], off
	s_nop 0
	s_nop 0
	v_add_u32_e32 v33, 0xa0, v146
	v_ashrrev_i32_e32 v33, 4, v33
	v_add_u32_e32 v34, v33, v147
	v_add_u32_e32 v33, v158, v33
	v_mad_i64_i32 v[34:35], s[36:37], v34, s59, v[136:137]
	v_mad_i64_i32 v[36:37], s[36:37], v33, s59, v[136:137]
	v_mov_b32_e32 v32, v252
	v_fmamk_f32 v32, v32, 0x3a800000, v155
	v_rsq_f32_e32 v32, v32
	s_nop 0
	v_pk_mul_f32 v[30:31], v[30:31], v[32:33] op_sel_hi:[1,0]
	v_pk_mul_f32 v[28:29], v[28:29], v[32:33] op_sel_hi:[1,0]
	v_pk_mul_f32 v[26:27], v[26:27], v[32:33] op_sel_hi:[1,0]
	v_pk_mul_f32 v[24:25], v[24:25], v[32:33] op_sel_hi:[1,0]
	v_pk_mul_f32 v[22:23], v[22:23], v[32:33] op_sel_hi:[1,0]
	v_pk_mul_f32 v[20:21], v[20:21], v[32:33] op_sel_hi:[1,0]
	v_pk_mul_f32 v[38:39], v[18:19], v[32:33] op_sel_hi:[1,0]
	v_pk_mul_f32 v[32:33], v[16:17], v[32:33] op_sel_hi:[1,0]
	v_cvt_pk_bf16_f32 v16, v28, v29
	v_cvt_pk_bf16_f32 v17, v30, v31
	v_cvt_pk_bf16_f32 v18, v24, v25
	v_cvt_pk_bf16_f32 v19, v26, v27
	global_store_dwordx4 v[34:35], v[16:19], off
	s_nop 1
	v_cvt_pk_bf16_f32 v16, v20, v21
	v_cvt_pk_bf16_f32 v17, v22, v23
	v_cvt_pk_bf16_f32 v18, v32, v33
	v_cvt_pk_bf16_f32 v19, v38, v39
	global_store_dwordx4 v[36:37], v[16:19], off
	s_nop 0
	s_nop 0
	v_add_u32_e32 v17, 0xb0, v146
	v_ashrrev_i32_e32 v17, 4, v17
	v_add_u32_e32 v18, v17, v147
	v_add_u32_e32 v17, v158, v17
	v_mad_i64_i32 v[18:19], s[4:5], v18, s59, v[136:137]
	v_mad_i64_i32 v[20:21], s[4:5], v17, s59, v[136:137]
	s_mov_b64 s[4:5], -1
	v_mov_b32_e32 v16, v253
	v_fmamk_f32 v16, v16, 0x3a800000, v155
	v_rsq_f32_e32 v16, v16
	s_nop 0
	v_pk_mul_f32 v[14:15], v[14:15], v[16:17] op_sel_hi:[1,0]
	v_pk_mul_f32 v[12:13], v[12:13], v[16:17] op_sel_hi:[1,0]
	v_pk_mul_f32 v[10:11], v[10:11], v[16:17] op_sel_hi:[1,0]
	v_pk_mul_f32 v[8:9], v[8:9], v[16:17] op_sel_hi:[1,0]
	v_pk_mul_f32 v[6:7], v[6:7], v[16:17] op_sel_hi:[1,0]
	v_pk_mul_f32 v[4:5], v[4:5], v[16:17] op_sel_hi:[1,0]
	v_pk_mul_f32 v[22:23], v[2:3], v[16:17] op_sel_hi:[1,0]
	v_pk_mul_f32 v[16:17], v[0:1], v[16:17] op_sel_hi:[1,0]
	v_cvt_pk_bf16_f32 v0, v12, v13
	v_cvt_pk_bf16_f32 v1, v14, v15
	v_cvt_pk_bf16_f32 v2, v8, v9
	v_cvt_pk_bf16_f32 v3, v10, v11
	global_store_dwordx4 v[18:19], v[0:3], off
	s_nop 1
	v_cvt_pk_bf16_f32 v0, v4, v5
	v_cvt_pk_bf16_f32 v1, v6, v7
	v_cvt_pk_bf16_f32 v2, v16, v17
	v_cvt_pk_bf16_f32 v3, v22, v23
	global_store_dwordx4 v[20:21], v[0:3], off
	s_cbranch_vccnz .LBB0_894
	s_andn2_b64 vcc, exec, s[8:9]
	s_cbranch_vccnz .LBB0_893
	s_barrier
	s_branch .LBB0_893
